# multi-unit GEMM phases: workgroups start staggered in 4 groups ((bx>>3)&3) x s_sleep 28 to desynchronize epilogue store bursts
# baseline (speedup 1.0000x reference)
.LBB0_116:
	s_bfe_u32 s98, s2, 0x20003
	s_cmp_eq_u32 s98, 0
	s_cbranch_scc1 .Lstgp1_done
.Lstgp1_loop:
	s_sleep 28
	s_add_i32 s98, s98, -1
	s_cmp_lg_u32 s98, 0
	s_cbranch_scc1 .Lstgp1_loop

.LBB0_903:
	s_lshl_b32 s96, s95, 1
	s_add_i32 s4, s96, 7
	s_cmp_le_i32 s79, s4
	s_cselect_b64 s[0:1], -1, 0
	s_cmp_lt_i32 s4, s78
	s_cselect_b64 s[4:5], -1, 0
	s_and_b64 s[0:1], s[0:1], s[4:5]
	s_andn2_b64 vcc, exec, s[0:1]
	s_cbranch_vccnz .LBB0_1049
	s_bfe_u32 s98, s2, 0x20003
	s_cmp_eq_u32 s98, 0
	s_cbranch_scc1 .Lstgcg_done

.Lstgcg_done:
	s_mov_b64 s[4:5], s[92:93]
	v_mbcnt_lo_u32_b32 v0, -1, 0
	v_mbcnt_hi_u32_b32 v0, -1, v0
	s_mov_b32 s14, s95
	v_add_u32_e32 v2, s37, v0
	s_cmp_lt_i32 s14, 2
	s_cselect_b64 s[12:13], -1, 0
	s_load_dwordx2 s[8:9], s[4:5], 0x70
	s_and_b64 s[4:5], s[12:13], exec
	s_cselect_b32 s58, 11, 10
	s_lshl_b32 s4, 1, s58
	s_add_i32 s60, s58, -8
	s_lshr_b32 s59, s4, 8
	s_lshl_b32 s5, 3, s60
	s_lshr_b32 s6, s4, 7
	s_cmp_gt_i32 s14, 1
	s_cselect_b32 s30, s5, s6
	s_lshl_b32 s44, s30, 6
	s_lshr_b32 s46, s4, 2
	s_mov_b32 s45, s57
	s_sub_u32 s15, 0, s44
	s_mov_b32 s47, s57
	s_subb_u32 s19, 0, 0
	s_mov_b32 s18, 0
	v_mov_b64_e32 v[0:1], s[44:45]
	s_mov_b64 s[6:7], s[2:3]
	s_cmp_lg_u32 s52, 0x100
	s_cbranch_scc1 .LBB0_907
	s_add_i32 s18, s44, s46
	s_sub_i32 s18, s18, s2
	s_add_i32 s18, s18, 0xff
	s_lshr_b32 s18, s18, 8
	s_cmp_gt_u32 s18, 15
	s_cbranch_scc1 .Lnu_generic
	s_mov_b64 s[4:5], 0
	s_branch .LBB0_917
